# in-proj layer0 epilogue: hoist 8 rrow loads, single vmcnt wait
# baseline (speedup 1.0000x reference)
; DI unsigned pk2(float lo, float hi) { f32x2 x = {lo, hi}; return __builtin_bit_cast(unsigned, __builtin_convertvector(x, bf16x2_t)); }
;     __device__ __forceinline__ void operator()(const f32x4 (&acc)[2][2][4][2], const Unit& u, int wr, int wc, int fr, int fq) const {
;         const int row0 = u.pm * BM + wr * 64 + fr; const int col0 = u.pn * BM + wc * 32 + 8 * fq;
; #pragma unroll
;         for (int ai = 0; ai < 2; ++ai)
; #pragma unroll
;             for (int m = 0; m < 4; ++m) { const int row = row0 + ai * HALF + m * 16; const float rs = rrow[row]; u16* rowp = O + (size_t)row * NP + col0;
; #pragma unroll
;                 for (int bj = 0; bj < 2; ++bj) { const f32x4 v0 = acc[ai][bj][m][0] * rs, v1 = acc[ai][bj][m][1] * rs;
;                     u32x4 w; w.x = pk2(v0[0], v0[1]); w.y = pk2(v0[2], v0[3]); w.z = pk2(v1[0], v1[1]); w.w = pk2(v1[2], v1[3]);
;                     *(u32x4*)(rowp + bj * HALF) = w; } }
.LBB0_111:
	v_lshl_add_u32 v148, s35, 8, v156
	v_readlane_b32 s18, v252, 23
	v_ashrrev_i32_e32 v149, 31, v148
	v_readlane_b32 s19, v252, 24
	v_lshl_or_b32 v154, s34, 8, v158
	v_ashrrev_i32_e32 v155, 31, v154
	v_lshl_add_u64 v[150:151], v[148:149], 2, s[18:19]
	global_load_dword v202, v[150:151], off
	global_load_dword v204, v[150:151], off offset:64
	global_load_dword v206, v[150:151], off offset:128
	global_load_dword v208, v[150:151], off offset:192
	global_load_dword v210, v[150:151], off offset:512
	global_load_dword v212, v[150:151], off offset:576
	global_load_dword v214, v[150:151], off offset:640
	global_load_dword v216, v[150:151], off offset:704
	v_mov_b64_e32 v[152:153], s[56:57]
	v_mad_i64_i32 v[162:163], s[2:3], v148, s85, v[152:153]
	v_lshlrev_b64 v[154:155], 1, v[154:155]
	v_lshl_add_u64 v[162:163], v[162:163], 0, v[154:155]
	s_andn2_b64 vcc, exec, s[0:1]
	s_waitcnt vmcnt(0)
	v_pk_mul_f32 v[128:129], v[128:129], v[202:203] op_sel_hi:[1,0]
	v_pk_mul_f32 v[126:127], v[126:127], v[202:203] op_sel_hi:[1,0]
	v_pk_mul_f32 v[164:165], v[124:125], v[202:203] op_sel_hi:[1,0]
	v_pk_mul_f32 v[124:125], v[122:123], v[202:203] op_sel_hi:[1,0]
	v_cvt_pk_bf16_f32 v122, v126, v127
	v_cvt_pk_bf16_f32 v123, v128, v129
	v_cvt_pk_bf16_f32 v124, v124, v125
	v_cvt_pk_bf16_f32 v125, v164, v165
	global_store_dwordx4 v[162:163], v[122:125], off
	v_pk_mul_f32 v[120:121], v[120:121], v[202:203] op_sel_hi:[1,0]
	v_pk_mul_f32 v[118:119], v[118:119], v[202:203] op_sel_hi:[1,0]
	v_pk_mul_f32 v[122:123], v[116:117], v[202:203] op_sel_hi:[1,0]
	v_pk_mul_f32 v[116:117], v[114:115], v[202:203] op_sel_hi:[1,0]
	v_cvt_pk_bf16_f32 v114, v118, v119
	v_cvt_pk_bf16_f32 v115, v120, v121
	v_cvt_pk_bf16_f32 v116, v116, v117
	v_cvt_pk_bf16_f32 v117, v122, v123
	global_store_dwordx4 v[162:163], v[114:117], off offset:256
	s_nop 1
	v_or_b32_e32 v114, 16, v148
	v_ashrrev_i32_e32 v115, 31, v114
	v_mad_i64_i32 v[114:115], s[2:3], v114, s85, v[152:153]
	v_lshl_add_u64 v[114:115], v[114:115], 0, v[154:155]
	v_pk_mul_f32 v[112:113], v[112:113], v[204:205] op_sel_hi:[1,0]
	v_pk_mul_f32 v[110:111], v[110:111], v[204:205] op_sel_hi:[1,0]
	v_pk_mul_f32 v[118:119], v[108:109], v[204:205] op_sel_hi:[1,0]
	v_pk_mul_f32 v[108:109], v[106:107], v[204:205] op_sel_hi:[1,0]
	v_cvt_pk_bf16_f32 v106, v110, v111
	v_cvt_pk_bf16_f32 v107, v112, v113
	v_cvt_pk_bf16_f32 v108, v108, v109
	v_cvt_pk_bf16_f32 v109, v118, v119
	global_store_dwordx4 v[114:115], v[106:109], off
	v_pk_mul_f32 v[104:105], v[104:105], v[204:205] op_sel_hi:[1,0]
	v_pk_mul_f32 v[102:103], v[102:103], v[204:205] op_sel_hi:[1,0]
	v_pk_mul_f32 v[106:107], v[100:101], v[204:205] op_sel_hi:[1,0]
	v_pk_mul_f32 v[100:101], v[98:99], v[204:205] op_sel_hi:[1,0]
	v_cvt_pk_bf16_f32 v98, v102, v103
	v_cvt_pk_bf16_f32 v99, v104, v105
	v_cvt_pk_bf16_f32 v100, v100, v101
	v_cvt_pk_bf16_f32 v101, v106, v107
	global_store_dwordx4 v[114:115], v[98:101], off offset:256
	s_nop 1
	v_or_b32_e32 v98, 32, v148
	v_ashrrev_i32_e32 v99, 31, v98
	v_mad_i64_i32 v[98:99], s[2:3], v98, s85, v[152:153]
	v_lshl_add_u64 v[98:99], v[98:99], 0, v[154:155]
	v_pk_mul_f32 v[96:97], v[96:97], v[206:207] op_sel_hi:[1,0]
	v_pk_mul_f32 v[94:95], v[94:95], v[206:207] op_sel_hi:[1,0]
	v_pk_mul_f32 v[102:103], v[92:93], v[206:207] op_sel_hi:[1,0]
	v_pk_mul_f32 v[92:93], v[90:91], v[206:207] op_sel_hi:[1,0]
	v_cvt_pk_bf16_f32 v90, v94, v95
	v_cvt_pk_bf16_f32 v91, v96, v97
	v_cvt_pk_bf16_f32 v92, v92, v93
	v_cvt_pk_bf16_f32 v93, v102, v103
	global_store_dwordx4 v[98:99], v[90:93], off
	v_pk_mul_f32 v[88:89], v[88:89], v[206:207] op_sel_hi:[1,0]
	v_pk_mul_f32 v[86:87], v[86:87], v[206:207] op_sel_hi:[1,0]
	v_pk_mul_f32 v[90:91], v[84:85], v[206:207] op_sel_hi:[1,0]
	v_pk_mul_f32 v[84:85], v[82:83], v[206:207] op_sel_hi:[1,0]
	v_cvt_pk_bf16_f32 v82, v86, v87
	v_cvt_pk_bf16_f32 v83, v88, v89
	v_cvt_pk_bf16_f32 v84, v84, v85
	v_cvt_pk_bf16_f32 v85, v90, v91
	global_store_dwordx4 v[98:99], v[82:85], off offset:256
	s_nop 1
	v_or_b32_e32 v82, 48, v148
	v_ashrrev_i32_e32 v83, 31, v82
	v_mad_i64_i32 v[82:83], s[2:3], v82, s85, v[152:153]
	v_lshl_add_u64 v[82:83], v[82:83], 0, v[154:155]
	s_mov_b64 s[18:19], -1
	v_pk_mul_f32 v[80:81], v[80:81], v[208:209] op_sel_hi:[1,0]
	v_pk_mul_f32 v[78:79], v[78:79], v[208:209] op_sel_hi:[1,0]
	v_pk_mul_f32 v[86:87], v[76:77], v[208:209] op_sel_hi:[1,0]
	v_pk_mul_f32 v[76:77], v[74:75], v[208:209] op_sel_hi:[1,0]
	v_cvt_pk_bf16_f32 v74, v78, v79
	v_cvt_pk_bf16_f32 v75, v80, v81
	v_cvt_pk_bf16_f32 v76, v76, v77
	v_cvt_pk_bf16_f32 v77, v86, v87
; DI unsigned pk2(float lo, float hi) { f32x2 x = {lo, hi}; return __builtin_bit_cast(unsigned, __builtin_convertvector(x, bf16x2_t)); }
;     __device__ __forceinline__ void operator()(const f32x4 (&acc)[2][2][4][2], const Unit& u, int wr, int wc, int fr, int fq) const {
;     ...
;             for (int m = 0; m < 4; ++m) { const int row = row0 + ai * HALF + m * 16; const float rs = rrow[row]; u16* rowp = O + (size_t)row * NP + col0;
; #pragma unroll
;                 for (int bj = 0; bj < 2; ++bj) { const f32x4 v0 = acc[ai][bj][m][0] * rs, v1 = acc[ai][bj][m][1] * rs;
;                     u32x4 w; w.x = pk2(v0[0], v0[1]); w.y = pk2(v0[2], v0[3]); w.z = pk2(v1[0], v1[1]); w.w = pk2(v1[2], v1[3]);
;                     *(u32x4*)(rowp + bj * HALF) = w; } }
	global_store_dwordx4 v[82:83], v[74:77], off
	v_pk_mul_f32 v[72:73], v[72:73], v[208:209] op_sel_hi:[1,0]
	v_pk_mul_f32 v[70:71], v[70:71], v[208:209] op_sel_hi:[1,0]
	v_pk_mul_f32 v[74:75], v[68:69], v[208:209] op_sel_hi:[1,0]
	v_pk_mul_f32 v[68:69], v[66:67], v[208:209] op_sel_hi:[1,0]
	v_cvt_pk_bf16_f32 v66, v70, v71
	v_cvt_pk_bf16_f32 v67, v72, v73
	v_cvt_pk_bf16_f32 v68, v68, v69
	v_cvt_pk_bf16_f32 v69, v74, v75
	global_store_dwordx4 v[82:83], v[66:69], off offset:256
	s_nop 0
	v_add_u32_e32 v67, 0x80, v148
	v_mad_i64_i32 v[68:69], s[2:3], v67, s85, v[152:153]
	v_lshl_add_u64 v[68:69], v[68:69], 0, v[154:155]
	v_pk_mul_f32 v[64:65], v[64:65], v[210:211] op_sel_hi:[1,0]
	v_pk_mul_f32 v[62:63], v[62:63], v[210:211] op_sel_hi:[1,0]
	v_pk_mul_f32 v[70:71], v[60:61], v[210:211] op_sel_hi:[1,0]
	v_pk_mul_f32 v[60:61], v[58:59], v[210:211] op_sel_hi:[1,0]
	v_cvt_pk_bf16_f32 v58, v62, v63
	v_cvt_pk_bf16_f32 v59, v64, v65
	v_cvt_pk_bf16_f32 v60, v60, v61
	v_cvt_pk_bf16_f32 v61, v70, v71
	global_store_dwordx4 v[68:69], v[58:61], off
	v_pk_mul_f32 v[56:57], v[56:57], v[210:211] op_sel_hi:[1,0]
	v_pk_mul_f32 v[54:55], v[54:55], v[210:211] op_sel_hi:[1,0]
	v_pk_mul_f32 v[58:59], v[52:53], v[210:211] op_sel_hi:[1,0]
	v_pk_mul_f32 v[52:53], v[50:51], v[210:211] op_sel_hi:[1,0]
	v_cvt_pk_bf16_f32 v50, v54, v55
	v_cvt_pk_bf16_f32 v51, v56, v57
	v_cvt_pk_bf16_f32 v52, v52, v53
	v_cvt_pk_bf16_f32 v53, v58, v59
	global_store_dwordx4 v[68:69], v[50:53], off offset:256
	s_nop 0
	v_add_u32_e32 v51, 0x90, v148
	v_mad_i64_i32 v[52:53], s[2:3], v51, s85, v[152:153]
	v_lshl_add_u64 v[52:53], v[52:53], 0, v[154:155]
	v_pk_mul_f32 v[48:49], v[48:49], v[212:213] op_sel_hi:[1,0]
	v_pk_mul_f32 v[46:47], v[46:47], v[212:213] op_sel_hi:[1,0]
	v_pk_mul_f32 v[54:55], v[44:45], v[212:213] op_sel_hi:[1,0]
	v_pk_mul_f32 v[44:45], v[42:43], v[212:213] op_sel_hi:[1,0]
	v_cvt_pk_bf16_f32 v42, v46, v47
	v_cvt_pk_bf16_f32 v43, v48, v49
	v_cvt_pk_bf16_f32 v44, v44, v45
	v_cvt_pk_bf16_f32 v45, v54, v55
	global_store_dwordx4 v[52:53], v[42:45], off
	v_pk_mul_f32 v[40:41], v[40:41], v[212:213] op_sel_hi:[1,0]
	v_pk_mul_f32 v[38:39], v[38:39], v[212:213] op_sel_hi:[1,0]
	v_pk_mul_f32 v[42:43], v[36:37], v[212:213] op_sel_hi:[1,0]
	v_pk_mul_f32 v[36:37], v[34:35], v[212:213] op_sel_hi:[1,0]
	v_cvt_pk_bf16_f32 v34, v38, v39
	v_cvt_pk_bf16_f32 v35, v40, v41
	v_cvt_pk_bf16_f32 v36, v36, v37
	v_cvt_pk_bf16_f32 v37, v42, v43
	global_store_dwordx4 v[52:53], v[34:37], off offset:256
	s_nop 0
	v_add_u32_e32 v35, 0xa0, v148
	v_mad_i64_i32 v[36:37], s[2:3], v35, s85, v[152:153]
	v_lshl_add_u64 v[36:37], v[36:37], 0, v[154:155]
	v_pk_mul_f32 v[32:33], v[32:33], v[214:215] op_sel_hi:[1,0]
	v_pk_mul_f32 v[30:31], v[30:31], v[214:215] op_sel_hi:[1,0]
	v_pk_mul_f32 v[38:39], v[28:29], v[214:215] op_sel_hi:[1,0]
	v_pk_mul_f32 v[28:29], v[26:27], v[214:215] op_sel_hi:[1,0]
	v_cvt_pk_bf16_f32 v26, v30, v31
	v_cvt_pk_bf16_f32 v27, v32, v33
	v_cvt_pk_bf16_f32 v28, v28, v29
	v_cvt_pk_bf16_f32 v29, v38, v39
	global_store_dwordx4 v[36:37], v[26:29], off
	v_pk_mul_f32 v[24:25], v[24:25], v[214:215] op_sel_hi:[1,0]
	v_pk_mul_f32 v[22:23], v[22:23], v[214:215] op_sel_hi:[1,0]
	v_pk_mul_f32 v[26:27], v[20:21], v[214:215] op_sel_hi:[1,0]
	v_pk_mul_f32 v[20:21], v[18:19], v[214:215] op_sel_hi:[1,0]
	v_cvt_pk_bf16_f32 v18, v22, v23
	v_cvt_pk_bf16_f32 v19, v24, v25
	v_cvt_pk_bf16_f32 v20, v20, v21
	v_cvt_pk_bf16_f32 v21, v26, v27
	global_store_dwordx4 v[36:37], v[18:21], off offset:256
	s_nop 0
	v_add_u32_e32 v19, 0xb0, v148
	v_mad_i64_i32 v[20:21], s[2:3], v19, s85, v[152:153]
	v_lshl_add_u64 v[20:21], v[20:21], 0, v[154:155]
	v_pk_mul_f32 v[16:17], v[16:17], v[216:217] op_sel_hi:[1,0]
	v_pk_mul_f32 v[14:15], v[14:15], v[216:217] op_sel_hi:[1,0]
	v_pk_mul_f32 v[22:23], v[12:13], v[216:217] op_sel_hi:[1,0]
	v_pk_mul_f32 v[12:13], v[10:11], v[216:217] op_sel_hi:[1,0]
	v_cvt_pk_bf16_f32 v10, v14, v15
	v_cvt_pk_bf16_f32 v11, v16, v17
	v_cvt_pk_bf16_f32 v12, v12, v13
	v_cvt_pk_bf16_f32 v13, v22, v23
	global_store_dwordx4 v[20:21], v[10:13], off
	v_pk_mul_f32 v[8:9], v[8:9], v[216:217] op_sel_hi:[1,0]
	v_pk_mul_f32 v[6:7], v[6:7], v[216:217] op_sel_hi:[1,0]
	v_pk_mul_f32 v[10:11], v[4:5], v[216:217] op_sel_hi:[1,0]
	v_pk_mul_f32 v[4:5], v[2:3], v[216:217] op_sel_hi:[1,0]
	v_cvt_pk_bf16_f32 v2, v6, v7
	v_cvt_pk_bf16_f32 v3, v8, v9
	v_cvt_pk_bf16_f32 v4, v4, v5
	v_cvt_pk_bf16_f32 v5, v10, v11
	global_store_dwordx4 v[20:21], v[2:5], off offset:256
	s_cbranch_vccnz .LBB0_104
	s_andn2_b64 vcc, exec, s[6:7]
	s_cbranch_vccnz .LBB0_103
	s_barrier
	s_branch .LBB0_103
